# differential attention: bias-table base constant set only in the near-tile paths (one SALU less per far tile)
# baseline (speedup 1.0000x reference)
; #define LAS __attribute__((address_space(3)))
; __device__ __forceinline__ f32x16 mma32(const h16x8 a, const h16x8 b, const f32x16 c) { return __builtin_amdgcn_mfma_f32_32x32x16_f16(a, b, c, 0, 0, 0); }
; __device__ __forceinline__ void diff_attn_item(CParams& p, int j, int layer, LAS unsigned char* lds, int b, int h, int qb, int tid_in, int lane_in, int wave) {
;     ...
;         const int k0 = kt * 64; const int cur = kt & 1;
;         const LAS h16* Ks = Ks0 + cur * 8704; const LAS h16* Vt = Vt0 + cur * 9216;
;         if (kt + 1 < nkt) ATT_STAGE(cur ^ 1, 512 + h * 128, 1024 + h * 128, kt + 2);
;         if (!(k0 > q0 + 31)) {
;         f32x16 sc[2];
; #pragma unroll
;         for (int sub = 0; sub < 2; ++sub) {
; #pragma unroll
;             for (int i = 0; i < 16; ++i) sc[sub][i] = 0.f;
; #pragma unroll
;             for (int s = 0; s < 4; ++s) sc[sub] = mma32(*(const LAS h16x8*)(Ks + (32 * sub + r) * 136 + mp * 64 + 16 * s + 8 * hh), qf[s], sc[sub]);
;         }
;         float mx = -INFINITY;
;         if (k0 + 63 + 128 <= q0) {
;             const float bfar = bdl[128];
; #pragma unroll
;             for (int sub = 0; sub < 2; ++sub)
; #pragma unroll
;                 for (int i = 0; i < 16; ++i) { sc[sub][i] += bfar; mx = fmaxf(mx, sc[sub][i]); }
;         } else {
; #pragma unroll
;             for (int sub = 0; sub < 2; ++sub)
; #pragma unroll
;                 for (int i = 0; i < 16; ++i) { const int kp = k0 + 32 * sub + (i & 3) + 8 * (i >> 2) + 4 * hh; const int dist = qp - kp;
;                     const float v = dist < 0 ? -INFINITY : sc[sub][i] + bdl[dist < 128 ? dist : 128]; sc[sub][i] = v; mx = fmaxf(mx, v); }
.LdiffA_top:
	s_mul_i32 s6, s41, 0x4400
	v_add_u32_e32 v214, s6, v211
	ds_read_b128 v[66:69], v214 offset:0
	ds_read_b128 v[70:73], v214 offset:32
	ds_read_b128 v[74:77], v214 offset:64
	ds_read_b128 v[78:81], v214 offset:96
	ds_read_b128 v[82:85], v214 offset:8704
	ds_read_b128 v[86:89], v214 offset:8736
	ds_read_b128 v[90:93], v214 offset:8768
	ds_read_b128 v[94:97], v214 offset:8800
	s_mul_i32 s12, s41, 0x4800
	v_add3_u32 v215, v195, v196, s12
	v_readfirstlane_b32 s6, v199
	s_waitcnt lgkmcnt(4)
	v_mfma_f32_32x32x16_f16 v[162:177], v[66:69], v[110:113], 0
	v_mfma_f32_32x32x16_f16 v[162:177], v[70:73], v[106:109], v[162:177]
	v_mfma_f32_32x32x16_f16 v[162:177], v[74:77], v[102:105], v[162:177]
	v_mfma_f32_32x32x16_f16 v[162:177], v[78:81], v[98:101], v[162:177]
	s_waitcnt lgkmcnt(0)
	v_mfma_f32_32x32x16_f16 v[228:243], v[82:85], v[110:113], 0
	v_mfma_f32_32x32x16_f16 v[228:243], v[86:89], v[106:109], v[228:243]
	v_mfma_f32_32x32x16_f16 v[228:243], v[90:93], v[102:105], v[228:243]
	v_mfma_f32_32x32x16_f16 v[228:243], v[94:97], v[98:101], v[228:243]
	s_sub_u32 s6, s6, s40
	s_add_u32 s6, s6, 0xbf
	s_cmp_ge_i32 s6, 0xbf
	s_cbranch_scc1 .LdiffA_far
	s_andn2_b32 s12, s6, 32
	s_cmp_eq_u32 s12, 64
	s_cbranch_scc1 .LdiffA_mid
	s_mov_b32 s7, 0x11800
	s_movk_i32 s12, 0x80
	v_add_u32_e32 v66, 59, v212
	v_med3_i32 v66, v66, 0, s12
	v_lshl_add_u32 v66, v66, 2, s7
	ds_read_b32 v66, v66
	v_add_u32_e32 v67, 58, v212
	v_med3_i32 v67, v67, 0, s12
	v_lshl_add_u32 v67, v67, 2, s7
	ds_read_b32 v67, v67
	v_add_u32_e32 v68, 57, v212
	v_med3_i32 v68, v68, 0, s12
	v_lshl_add_u32 v68, v68, 2, s7
	ds_read_b32 v68, v68
	v_add_u32_e32 v69, 56, v212
	v_med3_i32 v69, v69, 0, s12
	v_lshl_add_u32 v69, v69, 2, s7
	ds_read_b32 v69, v69
	v_add_u32_e32 v70, 51, v212
	v_med3_i32 v70, v70, 0, s12
	v_lshl_add_u32 v70, v70, 2, s7
	ds_read_b32 v70, v70
	v_add_u32_e32 v71, 50, v212
	v_med3_i32 v71, v71, 0, s12
	v_lshl_add_u32 v71, v71, 2, s7
	ds_read_b32 v71, v71
	v_add_u32_e32 v72, 49, v212
	v_med3_i32 v72, v72, 0, s12
	v_lshl_add_u32 v72, v72, 2, s7
	ds_read_b32 v72, v72
	v_add_u32_e32 v73, 48, v212
	v_med3_i32 v73, v73, 0, s12
	v_lshl_add_u32 v73, v73, 2, s7
	ds_read_b32 v73, v73
	v_add_u32_e32 v74, 43, v212
	v_med3_i32 v74, v74, 0, s12
	v_lshl_add_u32 v74, v74, 2, s7
	ds_read_b32 v74, v74
	v_add_u32_e32 v75, 42, v212
	v_med3_i32 v75, v75, 0, s12
	v_lshl_add_u32 v75, v75, 2, s7
	ds_read_b32 v75, v75
	v_add_u32_e32 v76, 41, v212
	v_med3_i32 v76, v76, 0, s12
	v_lshl_add_u32 v76, v76, 2, s7
	ds_read_b32 v76, v76
	v_add_u32_e32 v77, 40, v212
	v_med3_i32 v77, v77, 0, s12
	v_lshl_add_u32 v77, v77, 2, s7
	ds_read_b32 v77, v77
	v_add_u32_e32 v78, 35, v212
	v_med3_i32 v78, v78, 0, s12
	v_lshl_add_u32 v78, v78, 2, s7
	ds_read_b32 v78, v78
	v_add_u32_e32 v79, 34, v212
	v_med3_i32 v79, v79, 0, s12
	v_lshl_add_u32 v79, v79, 2, s7
	ds_read_b32 v79, v79
	v_add_u32_e32 v80, 33, v212
	v_med3_i32 v80, v80, 0, s12
	v_lshl_add_u32 v80, v80, 2, s7
	ds_read_b32 v80, v80
	v_add_u32_e32 v81, 32, v212
	v_med3_i32 v81, v81, 0, s12
	v_lshl_add_u32 v81, v81, 2, s7
	ds_read_b32 v81, v81
	v_add_u32_e32 v82, 27, v212
	v_med3_i32 v82, v82, 0, s12
	v_lshl_add_u32 v82, v82, 2, s7
	ds_read_b32 v82, v82
	v_add_u32_e32 v83, 26, v212
	v_med3_i32 v83, v83, 0, s12
	v_lshl_add_u32 v83, v83, 2, s7
	ds_read_b32 v83, v83
	v_add_u32_e32 v84, 25, v212
	v_med3_i32 v84, v84, 0, s12
	v_lshl_add_u32 v84, v84, 2, s7
	ds_read_b32 v84, v84
	v_add_u32_e32 v85, 24, v212
	v_med3_i32 v85, v85, 0, s12
	v_lshl_add_u32 v85, v85, 2, s7
	ds_read_b32 v85, v85
	v_add_u32_e32 v86, 19, v212
	v_med3_i32 v86, v86, 0, s12
	v_lshl_add_u32 v86, v86, 2, s7
	ds_read_b32 v86, v86
	v_add_u32_e32 v87, 18, v212
	v_med3_i32 v87, v87, 0, s12
	v_lshl_add_u32 v87, v87, 2, s7
	ds_read_b32 v87, v87
	v_add_u32_e32 v88, 17, v212
	v_med3_i32 v88, v88, 0, s12
	v_lshl_add_u32 v88, v88, 2, s7
	ds_read_b32 v88, v88
	v_add_u32_e32 v89, 16, v212
	v_med3_i32 v89, v89, 0, s12
	v_lshl_add_u32 v89, v89, 2, s7
	ds_read_b32 v89, v89
	v_add_u32_e32 v90, 11, v212
	v_med3_i32 v90, v90, 0, s12
	v_lshl_add_u32 v90, v90, 2, s7
	ds_read_b32 v90, v90
	v_add_u32_e32 v91, 10, v212
	v_med3_i32 v91, v91, 0, s12
	v_lshl_add_u32 v91, v91, 2, s7
	ds_read_b32 v91, v91
	v_add_u32_e32 v92, 9, v212
	v_med3_i32 v92, v92, 0, s12
	v_lshl_add_u32 v92, v92, 2, s7
	ds_read_b32 v92, v92
	v_add_u32_e32 v93, 8, v212
	v_med3_i32 v93, v93, 0, s12
	v_lshl_add_u32 v93, v93, 2, s7
	ds_read_b32 v93, v93
	v_add_u32_e32 v94, 3, v212
	v_med3_i32 v94, v94, 0, s12
	v_lshl_add_u32 v94, v94, 2, s7
	ds_read_b32 v94, v94
	v_add_u32_e32 v95, 2, v212
	v_med3_i32 v95, v95, 0, s12
	v_lshl_add_u32 v95, v95, 2, s7
	ds_read_b32 v95, v95
	v_add_u32_e32 v96, 1, v212
	v_med3_i32 v96, v96, 0, s12
	v_lshl_add_u32 v96, v96, 2, s7
	ds_read_b32 v96, v96
	v_add_u32_e32 v97, 0, v212
	v_med3_i32 v97, v97, 0, s12
	v_lshl_add_u32 v97, v97, 2, s7
	ds_read_b32 v97, v97
	v_sub_u32_e32 v145, 0, v212
	v_mov_b32_e32 v144, 0xff800000
	s_nop 4
	s_waitcnt lgkmcnt(0)
; __device__ __forceinline__ void diff_attn_item(CParams& p, int j, int layer, LAS unsigned char* lds, int b, int h, int qb, int tid_in, int lane_in, int wave) {
;     ...
; #pragma unroll
;             for (int sub = 0; sub < 2; ++sub)
; #pragma unroll
;                 for (int i = 0; i < 16; ++i) { const int kp = k0 + 32 * sub + (i & 3) + 8 * (i >> 2) + 4 * hh; const int dist = qp - kp;
;                     const float v = dist < 0 ? -INFINITY : sc[sub][i] + bdl[dist < 128 ? dist : 128]; sc[sub][i] = v; mx = fmaxf(mx, v); }
	v_pk_add_f32 v[162:163], v[162:163], v[66:67]
	v_pk_add_f32 v[164:165], v[164:165], v[68:69]
	v_pk_add_f32 v[166:167], v[166:167], v[70:71]
	v_pk_add_f32 v[168:169], v[168:169], v[72:73]
	v_pk_add_f32 v[170:171], v[170:171], v[74:75]
	v_pk_add_f32 v[172:173], v[172:173], v[76:77]
	v_pk_add_f32 v[174:175], v[174:175], v[78:79]
	v_pk_add_f32 v[176:177], v[176:177], v[80:81]
	v_pk_add_f32 v[228:229], v[228:229], v[82:83]
	v_pk_add_f32 v[230:231], v[230:231], v[84:85]
	v_pk_add_f32 v[232:233], v[232:233], v[86:87]
	v_pk_add_f32 v[234:235], v[234:235], v[88:89]
	v_pk_add_f32 v[236:237], v[236:237], v[90:91]
	v_pk_add_f32 v[238:239], v[238:239], v[92:93]
	v_pk_add_f32 v[240:241], v[240:241], v[94:95]
	v_pk_add_f32 v[242:243], v[242:243], v[96:97]
	v_cmp_ge_i32_e64 s[46:47], 59, v145
	v_cmp_ge_i32_e64 s[48:49], 58, v145
	v_cmp_ge_i32_e64 s[50:51], 57, v145
	v_cndmask_b32_e64 v162, v144, v162, s[46:47]
	v_cmp_ge_i32_e64 s[52:53], 56, v145
	v_cndmask_b32_e64 v163, v144, v163, s[48:49]
	v_cmp_ge_i32_e64 s[46:47], 51, v145
	v_cndmask_b32_e64 v164, v144, v164, s[50:51]
	v_cmp_ge_i32_e64 s[48:49], 50, v145
	v_cndmask_b32_e64 v165, v144, v165, s[52:53]
	v_cmp_ge_i32_e64 s[50:51], 49, v145
	v_cndmask_b32_e64 v166, v144, v166, s[46:47]
	v_cmp_ge_i32_e64 s[52:53], 48, v145
	v_cndmask_b32_e64 v167, v144, v167, s[48:49]
	v_cmp_ge_i32_e64 s[46:47], 43, v145
	v_cndmask_b32_e64 v168, v144, v168, s[50:51]
	v_cmp_ge_i32_e64 s[48:49], 42, v145
	v_cndmask_b32_e64 v169, v144, v169, s[52:53]
	v_cmp_ge_i32_e64 s[50:51], 41, v145
	v_cndmask_b32_e64 v170, v144, v170, s[46:47]
	v_cmp_ge_i32_e64 s[52:53], 40, v145
	v_cndmask_b32_e64 v171, v144, v171, s[48:49]
	v_cmp_ge_i32_e64 s[46:47], 35, v145
	v_cndmask_b32_e64 v172, v144, v172, s[50:51]
	v_cmp_ge_i32_e64 s[48:49], 34, v145
	v_cndmask_b32_e64 v173, v144, v173, s[52:53]
	v_cmp_ge_i32_e64 s[50:51], 33, v145
	v_cndmask_b32_e64 v174, v144, v174, s[46:47]
	v_cmp_ge_i32_e64 s[52:53], 32, v145
	v_cndmask_b32_e64 v175, v144, v175, s[48:49]
	v_cmp_ge_i32_e64 s[46:47], 27, v145
	v_cndmask_b32_e64 v176, v144, v176, s[50:51]
	v_cmp_ge_i32_e64 s[48:49], 26, v145
	v_cndmask_b32_e64 v177, v144, v177, s[52:53]
	v_cmp_ge_i32_e64 s[50:51], 25, v145
	v_cndmask_b32_e64 v228, v144, v228, s[46:47]
	v_cmp_ge_i32_e64 s[52:53], 24, v145
	v_cndmask_b32_e64 v229, v144, v229, s[48:49]
	v_cmp_ge_i32_e64 s[46:47], 19, v145
	v_cndmask_b32_e64 v230, v144, v230, s[50:51]
	v_cmp_ge_i32_e64 s[48:49], 18, v145
	v_cndmask_b32_e64 v231, v144, v231, s[52:53]
	v_cmp_ge_i32_e64 s[50:51], 17, v145
	v_cndmask_b32_e64 v232, v144, v232, s[46:47]
	v_cmp_ge_i32_e64 s[52:53], 16, v145
	v_cndmask_b32_e64 v233, v144, v233, s[48:49]
	v_cmp_ge_i32_e64 s[46:47], 11, v145
	v_cndmask_b32_e64 v234, v144, v234, s[50:51]
	v_cmp_ge_i32_e64 s[48:49], 10, v145
	v_cndmask_b32_e64 v235, v144, v235, s[52:53]
	v_cmp_ge_i32_e64 s[50:51], 9, v145
	v_cndmask_b32_e64 v236, v144, v236, s[46:47]
	v_cmp_ge_i32_e64 s[52:53], 8, v145
	v_cndmask_b32_e64 v237, v144, v237, s[48:49]
	v_cmp_ge_i32_e64 s[46:47], 3, v145
	v_cndmask_b32_e64 v238, v144, v238, s[50:51]
	v_cmp_ge_i32_e64 s[48:49], 2, v145
	v_cndmask_b32_e64 v239, v144, v239, s[52:53]
	v_cmp_ge_i32_e64 s[50:51], 1, v145
	v_cndmask_b32_e64 v240, v144, v240, s[46:47]
	v_cmp_ge_i32_e64 s[52:53], 0, v145
	v_cndmask_b32_e64 v241, v144, v241, s[48:49]
	v_cndmask_b32_e64 v242, v144, v242, s[50:51]
	v_cndmask_b32_e64 v243, v144, v243, s[52:53]
	v_mov_b32_e32 v213, 0
	s_branch .LdiffA_max
.LdiffA_mid:
	s_mov_b32 s7, 0x11800
	v_lshl_add_u32 v214, v212, 2, s7
	ds_read_b32 v66, v214 offset:236
	ds_read_b32 v67, v214 offset:232
	ds_read_b32 v68, v214 offset:228
	ds_read_b32 v69, v214 offset:224
	ds_read_b32 v70, v214 offset:204
	ds_read_b32 v71, v214 offset:200
	ds_read_b32 v72, v214 offset:196
	ds_read_b32 v73, v214 offset:192
	ds_read_b32 v74, v214 offset:172
	ds_read_b32 v75, v214 offset:168
	ds_read_b32 v76, v214 offset:164
	ds_read_b32 v77, v214 offset:160
	ds_read_b32 v78, v214 offset:140
	ds_read_b32 v79, v214 offset:136
	ds_read_b32 v80, v214 offset:132
	ds_read_b32 v81, v214 offset:128
	ds_read_b32 v82, v214 offset:108
	ds_read_b32 v83, v214 offset:104
	ds_read_b32 v84, v214 offset:100
	ds_read_b32 v85, v214 offset:96
	ds_read_b32 v86, v214 offset:76
	ds_read_b32 v87, v214 offset:72
	ds_read_b32 v88, v214 offset:68
	ds_read_b32 v89, v214 offset:64
	ds_read_b32 v90, v214 offset:44
	ds_read_b32 v91, v214 offset:40
	ds_read_b32 v92, v214 offset:36
	ds_read_b32 v93, v214 offset:32
	ds_read_b32 v94, v214 offset:12
	ds_read_b32 v95, v214 offset:8
	ds_read_b32 v96, v214 offset:4
	ds_read_b32 v97, v214 offset:0
	v_mov_b32_e32 v213, 0
	s_nop 4
	s_waitcnt lgkmcnt(0)
	v_pk_add_f32 v[162:163], v[162:163], v[66:67]
	v_pk_add_f32 v[164:165], v[164:165], v[68:69]
	v_pk_add_f32 v[166:167], v[166:167], v[70:71]
	v_pk_add_f32 v[168:169], v[168:169], v[72:73]
	v_pk_add_f32 v[170:171], v[170:171], v[74:75]
	v_pk_add_f32 v[172:173], v[172:173], v[76:77]
	v_pk_add_f32 v[174:175], v[174:175], v[78:79]
	v_pk_add_f32 v[176:177], v[176:177], v[80:81]
	v_pk_add_f32 v[228:229], v[228:229], v[82:83]
	v_pk_add_f32 v[230:231], v[230:231], v[84:85]
	v_pk_add_f32 v[232:233], v[232:233], v[86:87]
	v_pk_add_f32 v[234:235], v[234:235], v[88:89]
	v_pk_add_f32 v[236:237], v[236:237], v[90:91]
	v_pk_add_f32 v[238:239], v[238:239], v[92:93]
	v_pk_add_f32 v[240:241], v[240:241], v[94:95]
	v_pk_add_f32 v[242:243], v[242:243], v[96:97]
	s_branch .LdiffA_max
